# ret_scan: cross term written with 4 dword stores per lane (neighbour-lane DPP swap) instead of 8 short stores; K^T/V^T addressed ws base + 32-bit offsets
# speedup vs baseline: 1.0335x; 1.0054x over previous
.LBB0_638:
	s_or_b64 exec, exec, s[10:11]
	s_and_b32 s0, s51, 56
	s_ashr_i32 s16, s4, 3
	s_or_b32 s1, s0, s16
	s_ashr_i32 s4, s1, 3
	s_and_b32 s17, s4, 3
	v_cvt_f32_ubyte0_e32 v1, s17
	v_sub_f32_e32 v1, 0xc0a00000, v1
	s_mov_b32 s0, 0xc2fc0000
	v_mov_b32_e32 v14, 0x42800000
	v_cmp_gt_f32_e32 vcc, s0, v1
	s_lshl_b32 s13, s16, 5
	s_and_b64 s[8:9], vcc, exec
	v_cndmask_b32_e32 v2, 0, v14, vcc
	v_add_f32_e32 v1, v1, v2
	v_exp_f32_e32 v1, v1
	s_cselect_b32 s5, 0xffffffc0, 0
	v_mov_b32_e32 v2, 0x42000000
	v_mov_b32_e32 v3, 0
	v_ldexp_f32 v1, v1, s5
	v_sub_f32_e32 v1, 1.0, v1
	s_mov_b32 s5, 0x800000
	v_cmp_gt_f32_e32 vcc, s5, v1
	s_and_b64 s[8:9], vcc, exec
	s_cselect_b32 s5, 32, 0
	v_ldexp_f32 v1, v1, s5
	v_log_f32_e32 v1, v1
	v_cndmask_b32_e32 v2, 0, v2, vcc
	v_and_b32_e32 v6, 0x3f00, v131
	v_mov_b32_e32 v7, v3
	v_sub_f32_e32 v1, v1, v2
	v_mul_f32_e32 v2, 0x43000000, v1
	v_cmp_gt_f32_e32 vcc, s0, v2
	s_and_b64 s[10:11], vcc, exec
	s_cselect_b32 s5, 0xffffffc0, 0
	v_cndmask_b32_e32 v2, 0, v14, vcc
	v_fmac_f32_e32 v2, 0x43000000, v1
	v_exp_f32_e32 v2, v2
	s_ashr_i32 s12, s1, 5
	s_and_b32 s14, s13, 0xe0
	s_movk_i32 s1, 0x2000
	v_ldexp_f32 v122, v2, s5
	s_ashr_i32 s5, s4, 31
	s_lshl_b64 s[10:11], s[4:5], 23
	s_add_u32 s18, s78, s10
	s_addc_u32 s19, s79, s11
	v_and_b32_e32 v2, 0xf0, v131
	v_lshl_add_u64 v[4:5], s[18:19], 0, v[2:3]
	s_mov_b64 s[4:5], 0x38000000
	v_lshl_add_u64 v[4:5], v[4:5], 0, s[4:5]
	v_lshl_add_u64 v[8:9], v[4:5], 0, v[6:7]
	v_add_co_u32_e32 v10, vcc, s1, v8
	s_movk_i32 s1, 0x6000
	s_nop 0
	v_addc_co_u32_e32 v11, vcc, 0, v9, vcc
	global_load_dwordx4 v[200:203], v[8:9], off
	global_load_dwordx4 v[204:207], v[10:11], off
	v_or_b32_e32 v10, 0x4000, v6
	v_mov_b32_e32 v11, v3
	v_add_co_u32_e32 v12, vcc, s1, v8
	v_lshl_add_u64 v[10:11], v[4:5], 0, v[10:11]
	s_nop 0
	v_addc_co_u32_e32 v13, vcc, 0, v9, vcc
	s_mov_b32 s1, 0xa000
	global_load_dwordx4 v[208:211], v[10:11], off
	global_load_dwordx4 v[212:215], v[12:13], off
	v_add_co_u32_e32 v12, vcc, s1, v8
	v_or_b32_e32 v10, 0x8000, v6
	v_mov_b32_e32 v11, v3
	v_addc_co_u32_e32 v13, vcc, 0, v9, vcc
	v_or_b32_e32 v6, 0xc000, v6
	s_mov_b32 s1, 0xe000
	v_lshl_add_u64 v[10:11], v[4:5], 0, v[10:11]
	v_lshl_add_u64 v[4:5], v[4:5], 0, v[6:7]
	v_add_co_u32_e32 v6, vcc, s1, v8
	v_lshrrev_b32_e32 v16, 4, v153
	global_load_dwordx4 v[216:219], v[10:11], off
	global_load_dwordx4 v[220:223], v[12:13], off
	v_addc_co_u32_e32 v7, vcc, 0, v9, vcc
	global_load_dwordx4 v[224:227], v[4:5], off
	global_load_dwordx4 v[228:231], v[6:7], off
	v_add_lshl_u32 v4, s14, v16, 8
	v_mov_b32_e32 v5, v3
	v_lshl_add_u64 v[6:7], s[18:19], 0, v[4:5]
	s_ashr_i32 s13, s12, 31
	v_lshl_add_u64 v[6:7], v[6:7], 0, v[2:3]
	s_brev_b32 s1, 60
	s_lshl_b64 s[4:5], s[12:13], 14
	v_add_co_u32_e32 v6, vcc, s1, v6
	s_lshl_b32 s1, s50, 4
	s_add_u32 s8, s4, s1
	s_addc_u32 s15, s5, 0
	v_or_b32_e32 v8, s8, v130
	v_mov_b32_e32 v9, s15
	v_lshlrev_b64 v[8:9], 13, v[8:9]
	s_mov_b32 s9, 0
	v_lshl_add_u64 v[10:11], s[6:7], 0, v[8:9]
	s_lshl_b32 s8, s17, 9
	v_addc_co_u32_e32 v7, vcc, 0, v7, vcc
	v_lshl_add_u64 v[10:11], v[10:11], 0, s[8:9]
	v_and_b32_e32 v12, 48, v152
	v_mov_b32_e32 v13, v3
	v_lshl_add_u64 v[10:11], v[10:11], 0, v[12:13]
	global_load_dwordx4 v[232:235], v[6:7], off
	global_load_dwordx4 v[90:93], v[10:11], off
	global_load_dwordx4 v[86:89], v[10:11], off offset:64
	global_load_dwordx4 v[82:85], v[10:11], off offset:128
	global_load_dwordx4 v[78:81], v[10:11], off offset:192
	global_load_dwordx4 v[62:65], v[10:11], off offset:256
	global_load_dwordx4 v[46:49], v[10:11], off offset:320
	global_load_dwordx4 v[30:33], v[10:11], off offset:384
	global_load_dwordx4 v[22:25], v[10:11], off offset:448
	v_lshrrev_b32_e32 v15, 4, v152
	v_lshl_or_b32 v134, v15, 2, s1
	v_or_b32_e32 v132, 1, v134
	v_cvt_f32_u32_e32 v7, v132
	v_or_b32_e32 v128, 2, v134
	v_not_b32_e32 v42, 63
	v_or_b32_e32 v124, 3, v134
	v_mul_f32_e32 v17, v1, v7
	v_cmp_gt_f32_e32 vcc, s0, v17
	v_and_b32_e32 v5, 48, v153
	s_add_i32 s6, 0, 0x13200
	v_cndmask_b32_e32 v17, 0, v14, vcc
	v_fmac_f32_e32 v17, v1, v7
	v_cvt_f32_u32_e32 v7, v128
	v_cndmask_b32_e32 v43, 0, v42, vcc
	v_exp_f32_e32 v17, v17
	s_and_b32 s1, s3, 0xffffffc0
	v_mul_f32_e32 v44, v1, v7
	v_cmp_gt_f32_e32 vcc, s0, v44
	v_ldexp_f32 v148, v17, v43
	v_add_u32_e32 v10, s6, v5
	v_cndmask_b32_e32 v44, 0, v14, vcc
	v_fmac_f32_e32 v44, v1, v7
	v_exp_f32_e32 v7, v44
	v_cndmask_b32_e32 v17, 0, v42, vcc
	v_cvt_f32_u32_e32 v44, v124
	s_add_i32 s6, s6, s1
	v_ldexp_f32 v145, v7, v17
	v_add_u32_e32 v17, 4, v134
	v_cvt_f32_u32_e32 v17, v17
	v_mul_f32_e32 v7, v1, v44
	v_cmp_gt_f32_e32 vcc, s0, v7
	v_lshl_or_b32 v6, s50, 5, v130
	v_mul_f32_e32 v43, v1, v17
	v_cndmask_b32_e32 v7, 0, v14, vcc
	v_cmp_gt_f32_e64 s[0:1], s0, v43
	v_fmac_f32_e32 v7, v1, v44
	v_exp_f32_e32 v7, v7
	v_cndmask_b32_e64 v14, 0, v14, s[0:1]
	v_fmac_f32_e32 v14, v1, v17
	v_exp_f32_e32 v1, v14
	v_cndmask_b32_e32 v14, 0, v42, vcc
	v_ldexp_f32 v144, v7, v14
	v_cndmask_b32_e64 v7, 0, v42, s[0:1]
	v_ldexp_f32 v1, v1, v7
	v_add_u32_e32 v7, 0x200, v153
	v_lshrrev_b32_e32 v7, 4, v7
	v_mul_u32_u24_e32 v7, 0x110, v7
	v_add3_u32 v133, 0, v7, v2
	v_add_u32_e32 v7, 0x600, v153
	v_lshrrev_b32_e32 v7, 4, v7
	v_mul_u32_u24_e32 v7, 0x110, v7
	v_add3_u32 v149, 0, v7, v2
	v_add_u32_e32 v7, 0xa00, v153
	v_lshrrev_b32_e32 v7, 4, v7
	v_mul_u32_u24_e32 v7, 0x110, v7
	v_add3_u32 v150, 0, v7, v2
	v_add_u32_e32 v7, 0xe00, v153
	s_movk_i32 s0, 0x110
	v_lshrrev_b32_e32 v7, 4, v7
	s_add_i32 s7, 0, 0x11000
	v_mul_lo_u32 v14, v6, s0
	v_mul_u32_u24_e32 v6, 0x110, v16
	v_mul_u32_u24_e32 v7, 0x110, v7
	v_mov_b32_e32 v135, v3
	v_add3_u32 v125, 0, v6, v2
	v_add3_u32 v151, 0, v7, v2
	v_add3_u32 v154, s7, v6, v2
	s_lshl_b64 s[0:1], s[12:13], 26
	v_lshlrev_b64 v[6:7], 12, v[134:135]
	v_lshl_add_u64 v[136:137], s[0:1], 0, v[6:7]
	s_lshl_b32 s0, s16, 6
	v_or_b32_e32 v2, s8, v136
	s_and_b32 s0, s0, 0x1c0
	v_lshlrev_b32_e32 v6, 1, v130
	v_or3_b32 v136, v2, s0, v6
	v_lshl_or_b32 v2, v130, 4, s10
	v_or_b32_e32 v138, v2, v4
	v_mov_b32_e32 v139, s11
	s_mov_b64 s[0:1], 0x3c010000
	v_add_u32_e32 v11, 0, v5
	v_add_u32_e32 v12, s7, v5
	v_lshl_add_u32 v13, v15, 3, s6
	v_mul_u32_u24_e32 v15, 0x210, v130
	v_mul_u32_u24_e32 v17, 0x110, v130
	v_lshl_add_u64 v[140:141], v[138:139], 0, s[0:1]
	v_or3_b32 v8, v8, s8, v5
	s_mov_b64 s[0:1], 0x1c100100
	s_lshl_b32 s15, s17, 8
	v_mov_b32_e32 v126, v122
	v_mov_b32_e32 v127, v122
	v_lshl_or_b32 v138, v16, 8, v2
	v_lshl_add_u64 v[142:143], v[8:9], 0, s[0:1]
	s_movk_i32 s10, 0x7f
	s_mov_b32 s11, 0x38010000
	s_mov_b32 s12, 0x38012000
	s_mov_b32 s13, 0x38014000
	s_mov_b32 s16, 0x38016000
	s_mov_b32 s17, 0x38018000
	s_mov_b32 s18, 0x3801a000
	s_mov_b32 s19, 0x3801c000
	s_mov_b32 s20, 0x3801e000
	s_movk_i32 s21, 0x7fff
	s_mov_b32 s22, 0xf000000
	s_mov_b32 s23, 0xf001000
	s_mov_b32 s24, 0xf002000
	s_mov_b32 s25, 0xf003000
	s_mov_b32 s26, 0xffff0000
	s_mov_b64 s[0:1], 0x80000
	s_mov_b64 s[6:7], 0x10000
	s_mov_b64 s[8:9], 0x100000
	v_add_u32_e32 v129, v10, v15
	v_add_u32_e32 v146, v11, v14
	v_add_u32_e32 v147, v12, v17
	v_add_u32_e32 v131, v13, v15
	v_mov_b32_e32 v2, v3
	v_mov_b32_e32 v4, v3
	v_mov_b32_e32 v5, v3
	v_mov_b32_e32 v6, v3
	v_mov_b32_e32 v7, v3
	v_mov_b32_e32 v8, v3
	v_mov_b32_e32 v9, v3
	v_mov_b32_e32 v10, v3
	v_mov_b32_e32 v11, v3
	v_mov_b32_e32 v12, v3
	v_mov_b32_e32 v13, v3
	v_mov_b32_e32 v14, v3
	v_mov_b32_e32 v15, v3
	v_mov_b32_e32 v16, v3
	v_mov_b32_e32 v17, v3
	v_add_u32_e32 v240, s11, v138
	v_add_u32_e32 v241, s12, v138
	v_add_u32_e32 v242, s13, v138
	v_add_u32_e32 v243, s16, v138
	v_add_u32_e32 v244, s17, v138
	v_add_u32_e32 v245, s18, v138
	v_add_u32_e32 v246, s19, v138
	v_add_u32_e32 v247, s20, v138
	v_mov_b32_e32 v248, v140
	v_and_b32_e32 v36, 1, v152
	v_sub_u32_e32 v249, 0, v36
	v_mov_b32_e32 v250, 0x7060302
	v_mul_u32_u24_e32 v36, 30, v36
	v_add_u32_e32 v136, v136, v36
	s_waitcnt vmcnt(0)
.LBB0_639:
	s_waitcnt vmcnt(12)
	ds_write_b128 v125, v[200:203]
	ds_write_b128 v133, v[204:207]
	ds_write_b128 v125, v[208:211] offset:17408
	ds_write_b128 v149, v[212:215]
	ds_write_b128 v125, v[216:219] offset:34816
	ds_write_b128 v150, v[220:223]
	ds_write_b128 v125, v[224:227] offset:52224
	ds_write_b128 v151, v[228:231]
	ds_write_b128 v154, v[232:235]
	s_waitcnt lgkmcnt(0)
	global_load_dwordx4 v[200:203], v240, s[78:79]
	global_load_dwordx4 v[204:207], v241, s[78:79]
	global_load_dwordx4 v[208:211], v242, s[78:79]
	global_load_dwordx4 v[212:215], v243, s[78:79]
	global_load_dwordx4 v[216:219], v244, s[78:79]
	global_load_dwordx4 v[220:223], v245, s[78:79]
	global_load_dwordx4 v[224:227], v246, s[78:79]
	global_load_dwordx4 v[228:231], v247, s[78:79]
	global_load_dwordx4 v[232:235], v248, s[78:79]
	v_add_u32_e32 v240, s6, v240
	v_add_u32_e32 v241, s6, v241
	v_add_u32_e32 v242, s6, v242
	v_add_u32_e32 v243, s6, v243
	v_add_u32_e32 v244, s6, v244
	v_add_u32_e32 v245, s6, v245
	v_add_u32_e32 v246, s6, v246
	v_add_u32_e32 v247, s6, v247
	v_add_u32_e32 v248, s6, v248
	s_barrier
	s_waitcnt vmcnt(13)
	v_mov_b64_e32 v[100:101], v[64:65]
	v_mov_b64_e32 v[96:97], v[48:49]
	v_mov_b64_e32 v[52:53], v[32:33]
	v_mov_b64_e32 v[44:45], v[24:25]
	v_mov_b64_e32 v[98:99], v[62:63]
	v_mov_b64_e32 v[94:95], v[46:47]
	v_mov_b64_e32 v[50:51], v[30:31]
	v_mov_b64_e32 v[42:43], v[22:23]
	ds_read_b128 v[46:49], v129
	ds_read_b128 v[54:57], v129 offset:64
	ds_read_b128 v[62:65], v129 offset:8448
	ds_read_b128 v[66:69], v129 offset:8512
	ds_read_b128 v[70:73], v129 offset:128
	ds_read_b128 v[22:25], v129 offset:192
	ds_read_b128 v[74:77], v129 offset:8576
	ds_read_b128 v[30:33], v129 offset:8640
	ds_read_b128 v[18:21], v129 offset:256
	ds_read_b128 v[58:61], v129 offset:320
	ds_read_b128 v[26:29], v129 offset:8704
	ds_read_b128 v[118:121], v129 offset:8768
	ds_read_b128 v[110:113], v129 offset:384
	ds_read_b128 v[106:109], v129 offset:448
	ds_read_b128 v[114:117], v129 offset:8832
	ds_read_b128 v[102:105], v129 offset:8896
	s_waitcnt lgkmcnt(14)
	v_mfma_f32_16x16x32_bf16 v[46:49], v[90:93], v[46:49], 0
	ds_read_b128 v[156:159], v146
	ds_read_b128 v[160:163], v147
	v_mov_b32_e32 v123, v122
	v_lshl_add_u64 v[34:35], s[78:79], 0, v[138:139]
	s_waitcnt lgkmcnt(14)
	v_mfma_f32_16x16x32_bf16 v[62:65], v[90:93], v[62:65], 0
	ds_read_b128 v[90:93], v146 offset:64
	ds_read_b128 v[164:167], v146 offset:4352
	ds_read_b128 v[168:171], v146 offset:4416
	v_pk_mul_f32 v[6:7], v[126:127], v[6:7]
	v_pk_mul_f32 v[2:3], v[126:127], v[2:3]
	v_mfma_f32_16x16x32_bf16 v[46:49], v[86:89], v[54:57], v[46:49]
	ds_read_b128 v[54:57], v147 offset:64
	ds_read_b128 v[172:175], v147 offset:4352
	ds_read_b128 v[176:179], v147 offset:4416
	v_pk_mul_f32 v[8:9], v[122:123], v[8:9]
	v_pk_mul_f32 v[4:5], v[122:123], v[4:5]
	v_pk_mul_f32 v[10:11], v[126:127], v[10:11]
	s_waitcnt lgkmcnt(4)
	v_mfma_f32_16x16x32_bf16 v[6:9], v[164:167], v[160:163], v[6:9]
	v_mul_f32_e64 v12, v122, v12
	v_mul_f32_e64 v13, v123, v13
	v_pk_mul_f32 v[14:15], v[126:127], v[14:15]
	v_pk_mul_f32 v[16:17], v[122:123], v[16:17]
	s_waitcnt lgkmcnt(1)
	v_mfma_f32_16x16x32_bf16 v[2:5], v[164:167], v[172:175], v[2:5]
	v_add_co_u32_e32 v164, vcc, s11, v34
	v_lshl_add_u64 v[40:41], s[78:79], 0, v[136:137]
	s_nop 0
	v_addc_co_u32_e32 v165, vcc, 0, v35, vcc
	v_add_co_u32_e32 v166, vcc, s12, v34
	v_mfma_f32_16x16x32_bf16 v[10:13], v[156:159], v[172:175], v[10:13]
	s_nop 0
	v_addc_co_u32_e32 v167, vcc, 0, v35, vcc
	v_add_co_u32_e32 v172, vcc, s13, v34
	v_mfma_f32_16x16x32_bf16 v[6:9], v[168:171], v[54:57], v[6:9]
	s_nop 0
	v_addc_co_u32_e32 v173, vcc, 0, v35, vcc
	v_add_co_u32_e32 v174, vcc, s16, v34
	s_waitcnt lgkmcnt(0)
	v_mfma_f32_16x16x32_bf16 v[2:5], v[168:171], v[176:179], v[2:5]
	v_addc_co_u32_e32 v175, vcc, 0, v35, vcc
	v_add_co_u32_e32 v168, vcc, s17, v34
	v_mfma_f32_16x16x32_bf16 v[14:17], v[156:159], v[160:163], v[14:17]
	s_nop 0
	v_addc_co_u32_e32 v169, vcc, 0, v35, vcc
	v_add_co_u32_e32 v170, vcc, s18, v34
	v_mfma_f32_16x16x32_bf16 v[62:65], v[86:89], v[66:69], v[62:65]
	s_nop 0
	v_addc_co_u32_e32 v171, vcc, 0, v35, vcc
	ds_read_b128 v[66:69], v146 offset:128
	ds_read_b128 v[180:183], v146 offset:192
	v_mfma_f32_16x16x32_bf16 v[46:49], v[82:85], v[70:73], v[46:49]
	ds_read_b128 v[184:187], v146 offset:4480
	ds_read_b128 v[188:191], v146 offset:4544
	ds_read_b128 v[156:159], v147 offset:128
	ds_read_b128 v[192:195], v147 offset:192
	ds_read_b128 v[160:163], v147 offset:4480
	ds_read_b128 v[196:199], v147 offset:4544
	v_mfma_f32_16x16x32_bf16 v[10:13], v[90:93], v[176:179], v[10:13]
	v_add_co_u32_e32 v176, vcc, s19, v34
	v_lshl_add_u64 v[38:39], s[78:79], 0, v[140:141]
	s_nop 0
	v_addc_co_u32_e32 v177, vcc, 0, v35, vcc
	v_mfma_f32_16x16x32_bf16 v[14:17], v[90:93], v[54:57], v[14:17]
	v_add_co_u32_e32 v178, vcc, s20, v34
	v_lshl_add_u64 v[36:37], s[78:79], 0, v[142:143]
	v_mfma_f32_16x16x32_bf16 v[62:65], v[82:85], v[74:77], v[62:65]
	v_addc_co_u32_e32 v179, vcc, 0, v35, vcc
	global_load_dwordx4 v[90:93], v[36:37], off offset:-256
	global_load_dwordx4 v[86:89], v[36:37], off offset:-192
	v_mfma_f32_16x16x32_bf16 v[54:57], v[78:81], v[22:25], v[46:49]
	s_add_i32 s10, s10, -1
	v_lshl_add_u64 v[136:137], v[136:137], 0, s[0:1]
	v_lshl_add_u64 v[140:141], v[140:141], 0, s[6:7]
	s_waitcnt lgkmcnt(1)
	v_mfma_f32_16x16x32_bf16 v[10:13], v[66:69], v[160:163], v[10:13]
	v_lshl_add_u64 v[138:139], v[138:139], 0, s[6:7]
	v_lshl_add_u64 v[142:143], v[142:143], 0, s[8:9]
	s_cmp_lg_u32 s10, 0
	v_mfma_f32_16x16x32_bf16 v[2:5], v[184:187], v[160:163], v[2:5]
	v_add_co_u32_e32 v160, vcc, s22, v40
	v_add_u32_e32 v135, 0x2000, v131
	s_nop 0
	v_addc_co_u32_e32 v161, vcc, 0, v41, vcc
	v_mfma_f32_16x16x32_bf16 v[14:17], v[66:69], v[156:159], v[14:17]
	v_add_co_u32_e32 v162, vcc, s23, v40
	v_mfma_f32_16x16x32_bf16 v[74:77], v[78:81], v[30:33], v[62:65]
	s_nop 0
	v_addc_co_u32_e32 v163, vcc, 0, v41, vcc
	global_load_dwordx4 v[82:85], v[36:37], off offset:-128
	global_load_dwordx4 v[78:81], v[36:37], off offset:-64
	global_load_dwordx4 v[62:65], v[36:37], off
	v_mfma_f32_16x16x32_bf16 v[66:69], v[98:101], v[18:21], v[54:57]
	global_load_dwordx4 v[46:49], v[36:37], off offset:64
	global_load_dwordx4 v[30:33], v[36:37], off offset:128
	global_load_dwordx4 v[22:25], v[36:37], off offset:192
	v_mfma_f32_16x16x32_bf16 v[6:9], v[184:187], v[156:159], v[6:9]
	v_add_co_u32_e32 v184, vcc, s24, v40
	s_nop 1
	v_addc_co_u32_e32 v185, vcc, 0, v41, vcc
	v_mfma_f32_16x16x32_bf16 v[14:17], v[180:183], v[192:195], v[14:17]
	s_waitcnt lgkmcnt(0)
	v_mfma_f32_16x16x32_bf16 v[10:13], v[180:183], v[196:199], v[10:13]
	v_add_co_u32_e32 v180, vcc, s25, v40
	v_mfma_f32_16x16x32_bf16 v[98:101], v[98:101], v[26:29], v[74:77]
	s_nop 0
	v_addc_co_u32_e32 v181, vcc, 0, v41, vcc
	v_mfma_f32_16x16x32_bf16 v[156:159], v[94:97], v[58:61], v[66:69]
	s_nop 1
	v_mfma_f32_16x16x32_bf16 v[6:9], v[188:191], v[192:195], v[6:9]
	v_mfma_f32_16x16x32_bf16 v[2:5], v[188:191], v[196:199], v[2:5]
	v_mfma_f32_16x16x32_bf16 v[94:97], v[94:97], v[118:121], v[98:101]
	v_bfe_u32 v118, v10, 16, 1
	v_bfe_u32 v120, v12, 16, 1
	v_bfe_u32 v119, v11, 16, 1
	v_bfe_u32 v98, v14, 16, 1
	v_bfe_u32 v99, v15, 16, 1
	v_bfe_u32 v100, v16, 16, 1
	v_bfe_u32 v101, v17, 16, 1
	v_bfe_u32 v121, v13, 16, 1
	v_bfe_u32 v155, v6, 16, 1
	v_bfe_u32 v164, v7, 16, 1
	v_bfe_u32 v165, v8, 16, 1
	v_bfe_u32 v166, v9, 16, 1
	v_bfe_u32 v167, v2, 16, 1
	v_bfe_u32 v168, v3, 16, 1
	v_bfe_u32 v169, v4, 16, 1
	v_bfe_u32 v170, v5, 16, 1
	v_add3_u32 v98, v14, v98, s21
	v_add3_u32 v171, v15, v99, s21
	v_add3_u32 v99, v16, v100, s21
	v_add3_u32 v172, v17, v101, s21
	v_add3_u32 v100, v10, v118, s21
	v_add3_u32 v101, v12, v120, s21
	v_add3_u32 v118, v11, v119, s21
	v_add3_u32 v119, v13, v121, s21
	v_add3_u32 v120, v6, v155, s21
	v_add3_u32 v121, v7, v164, s21
	v_add3_u32 v155, v8, v165, s21
	v_add3_u32 v164, v9, v166, s21
	v_add3_u32 v165, v2, v167, s21
	v_add3_u32 v166, v3, v168, s21
	v_add3_u32 v167, v4, v169, s21
	v_add3_u32 v168, v5, v170, s21
	v_lshrrev_b32_e32 v169, 16, v98
	v_lshrrev_b32_e32 v170, 16, v99
	v_lshrrev_b32_e32 v173, 16, v100
	v_lshrrev_b32_e32 v174, 16, v101
	v_mfma_f32_16x16x32_bf16 v[98:101], v[50:53], v[110:113], v[156:159]
	v_lshrrev_b32_e32 v120, 16, v120
	v_lshrrev_b32_e32 v155, 16, v155
	v_lshrrev_b32_e32 v165, 16, v165
	v_mfma_f32_16x16x32_bf16 v[50:53], v[50:53], v[114:117], v[94:97]
	v_lshrrev_b32_e32 v156, 16, v167
	v_and_or_b32 v110, v171, s26, v169
	v_and_or_b32 v111, v172, s26, v170
	v_mfma_f32_16x16x32_bf16 v[94:97], v[42:45], v[106:109], v[98:101]
	v_and_or_b32 v114, v121, s26, v120
	v_and_or_b32 v115, v164, s26, v155
	v_and_or_b32 v112, v118, s26, v173
	v_mfma_f32_16x16x32_bf16 v[42:45], v[42:45], v[102:105], v[50:53]
	v_and_or_b32 v113, v119, s26, v174
	v_and_or_b32 v98, v166, s26, v165
	v_and_or_b32 v99, v168, s26, v156
	s_nop 0
	v_mul_f32_e32 v50, v148, v94
	v_mul_f32_e32 v51, v145, v95
	s_nop 1
	v_mul_f32_e32 v42, v148, v42
	v_mul_f32_e32 v43, v145, v43
	v_mul_f32_e32 v52, v144, v96
	v_mul_f32_e32 v44, v144, v44
	v_mul_f32_e32 v53, v1, v97
	v_mul_f32_e32 v45, v1, v45
	v_bfe_u32 v94, v50, 16, 1
	v_bfe_u32 v95, v42, 16, 1
	v_bfe_u32 v96, v51, 16, 1
	v_bfe_u32 v97, v43, 16, 1
	v_bfe_u32 v100, v52, 16, 1
	v_bfe_u32 v101, v44, 16, 1
	v_bfe_u32 v102, v53, 16, 1
	v_bfe_u32 v103, v45, 16, 1
	v_add3_u32 v50, v50, v94, s21
	v_add3_u32 v42, v42, v95, s21
	v_add3_u32 v51, v51, v96, s21
	v_add3_u32 v43, v43, v97, s21
	v_add3_u32 v52, v52, v100, s21
	v_add3_u32 v44, v44, v101, s21
	v_add3_u32 v53, v53, v102, s21
	v_add3_u32 v45, v45, v103, s21
	v_bfi_b32 v94, v249, v50, v42
	v_bfi_b32 v95, v249, v51, v43
	v_bfi_b32 v96, v249, v52, v44
	v_bfi_b32 v97, v249, v53, v45
	v_mov_b32_dpp v100, v94 quad_perm:[1,0,3,2] row_mask:0xf bank_mask:0xf
	v_mov_b32_dpp v101, v95 quad_perm:[1,0,3,2] row_mask:0xf bank_mask:0xf
	v_mov_b32_dpp v102, v96 quad_perm:[1,0,3,2] row_mask:0xf bank_mask:0xf
	v_mov_b32_dpp v103, v97 quad_perm:[1,0,3,2] row_mask:0xf bank_mask:0xf
	v_bfi_b32 v94, v249, v42, v100
	v_bfi_b32 v95, v249, v43, v101
	v_bfi_b32 v96, v249, v44, v102
	v_bfi_b32 v97, v249, v45, v103
	v_bfi_b32 v100, v249, v100, v50
	v_bfi_b32 v101, v249, v101, v51
	v_bfi_b32 v102, v249, v102, v52
	v_bfi_b32 v103, v249, v103, v53
	v_perm_b32 v94, v94, v100, v250
	v_perm_b32 v95, v95, v101, v250
	v_perm_b32 v96, v96, v102, v250
	v_perm_b32 v97, v97, v103, v250
	global_store_dword v[160:161], v94, off offset:2048
	global_store_dword v[162:163], v95, off offset:2048
	global_store_dword v[184:185], v96, off offset:2048
	global_store_dword v[180:181], v97, off offset:2048
	s_barrier
	ds_write2_b64 v131, v[110:111], v[114:115] offset1:4
	ds_write2_b64 v135, v[112:113], v[98:99] offset0:32 offset1:36
	s_cbranch_scc1 .LBB0_639
	s_waitcnt vmcnt(12)
	ds_write_b128 v125, v[200:203]
	ds_write_b128 v133, v[204:207]
	ds_write_b128 v125, v[208:211] offset:17408
	ds_write_b128 v149, v[212:215]
	ds_write_b128 v125, v[216:219] offset:34816
	ds_write_b128 v150, v[220:223]
	ds_write_b128 v125, v[224:227] offset:52224
	s_waitcnt vmcnt(4)
	ds_write_b128 v151, v[228:231]
	ds_write_b128 v154, v[232:235]
	s_waitcnt lgkmcnt(0)
	s_barrier
	ds_read_b128 v[18:21], v129
	ds_read_b128 v[26:29], v129 offset:64
	ds_read_b128 v[34:37], v129 offset:8448
	ds_read_b128 v[38:41], v129 offset:8512
	s_waitcnt lgkmcnt(3)
	v_mfma_f32_16x16x32_bf16 v[18:21], v[90:93], v[18:21], 0
	s_lshl_b32 s0, s15, 1
	s_add_u32 s0, s78, s0
	s_addc_u32 s1, s79, 0
	s_waitcnt lgkmcnt(1)
	v_mfma_f32_16x16x32_bf16 v[34:37], v[90:93], v[34:37], 0
	s_lshl_b32 s6, s14, 1
	s_add_u32 s0, s0, s6
	v_mov_b32_e32 v51, 0
	v_mfma_f32_16x16x32_bf16 v[18:21], v[86:89], v[26:29], v[18:21]
	s_addc_u32 s1, s1, 0
	v_lshlrev_b32_e32 v50, 1, v130
	v_mov_b32_e32 v135, v51
	s_waitcnt lgkmcnt(0)
	v_mfma_f32_16x16x32_bf16 v[26:29], v[86:89], v[38:41], v[34:37]
	s_nop 2
	ds_read_b128 v[34:37], v129 offset:128
	ds_read_b128 v[38:41], v129 offset:192
	s_or_b32 s4, s4, 0x3f80
	v_lshl_add_u64 v[52:53], s[0:1], 0, v[50:51]
	s_waitcnt lgkmcnt(1)
	v_mfma_f32_16x16x32_bf16 v[18:21], v[82:85], v[34:37], v[18:21]
	ds_read_b128 v[34:37], v129 offset:8576
	ds_read_b128 v[42:45], v129 offset:8640
	s_mov_b64 s[0:1], 0xf000800
	v_lshl_add_u64 v[54:55], v[52:53], 0, s[0:1]
	s_waitcnt lgkmcnt(1)
	v_mfma_f32_16x16x32_bf16 v[26:29], v[82:85], v[34:37], v[26:29]
	ds_read_b128 v[34:37], v129 offset:256
	s_movk_i32 s0, 0x7fff
	v_mov_b32_e32 v133, v51
	v_mfma_f32_16x16x32_bf16 v[18:21], v[78:81], v[38:41], v[18:21]
	v_mul_f32_e64 v16, v122, v16
	v_mul_f32_e64 v17, v123, v17
	v_pk_mul_f32 v[14:15], v[126:127], v[14:15]
	v_pk_mul_f32 v[8:9], v[122:123], v[8:9]
	s_waitcnt lgkmcnt(1)
	v_mfma_f32_16x16x32_bf16 v[26:29], v[78:81], v[42:45], v[26:29]
	ds_read_b128 v[38:41], v129 offset:8704
	ds_read_b128 v[42:45], v129 offset:320
	v_pk_mul_f32 v[6:7], v[126:127], v[6:7]
	v_pk_mul_f32 v[12:13], v[122:123], v[12:13]
	s_waitcnt lgkmcnt(2)
	v_mfma_f32_16x16x32_bf16 v[18:21], v[62:65], v[34:37], v[18:21]
	ds_read_b128 v[34:37], v129 offset:8768
	v_pk_mul_f32 v[10:11], v[126:127], v[10:11]
	v_mov_b32_e32 v125, v51
	s_waitcnt lgkmcnt(2)
	v_mfma_f32_16x16x32_bf16 v[26:29], v[62:65], v[38:41], v[26:29]
	ds_read_b128 v[38:41], v129 offset:384
	v_pk_mul_f32 v[4:5], v[122:123], v[4:5]
	v_pk_mul_f32 v[2:3], v[126:127], v[2:3]
	s_waitcnt lgkmcnt(2)
	v_mfma_f32_16x16x32_bf16 v[18:21], v[46:49], v[42:45], v[18:21]
	s_mov_b32 s1, 0xffff0000
	s_waitcnt lgkmcnt(1)
	v_mfma_f32_16x16x32_bf16 v[26:29], v[46:49], v[34:37], v[26:29]
	ds_read_b128 v[34:37], v129 offset:8832
	ds_read_b128 v[42:45], v129 offset:448
	s_waitcnt lgkmcnt(2)
	v_mfma_f32_16x16x32_bf16 v[18:21], v[30:33], v[38:41], v[18:21]
	ds_read_b128 v[38:41], v129 offset:8896
	v_mov_b32_e32 v129, v51
	s_waitcnt lgkmcnt(2)
	v_mfma_f32_16x16x32_bf16 v[26:29], v[30:33], v[34:37], v[26:29]
	v_lshl_add_u64 v[30:31], s[4:5], 0, v[134:135]
	v_lshlrev_b64 v[30:31], 12, v[30:31]
	s_waitcnt lgkmcnt(1)
	v_mfma_f32_16x16x32_bf16 v[18:21], v[22:25], v[42:45], v[18:21]
	s_waitcnt lgkmcnt(0)
	v_mfma_f32_16x16x32_bf16 v[22:25], v[22:25], v[38:41], v[26:29]
	s_nop 2
	v_lshl_add_u64 v[26:27], v[54:55], 0, v[30:31]
	s_nop 1
	v_mul_f32_e32 v18, v148, v18
	v_bfe_u32 v28, v18, 16, 1
	v_add3_u32 v18, v18, v28, s0
	global_store_short_d16_hi v[26:27], v18, off
	v_mul_f32_e32 v18, v148, v22
	v_bfe_u32 v22, v18, 16, 1
	v_add3_u32 v18, v18, v22, s0
	global_store_short_d16_hi v[26:27], v18, off offset:32
	ds_read_b128 v[26:29], v146
	v_lshl_add_u64 v[30:31], s[4:5], 0, v[132:133]
	v_lshlrev_b64 v[56:57], 12, v[30:31]
	ds_read_b128 v[30:33], v147
	ds_read_b128 v[34:37], v146 offset:4352
	ds_read_b128 v[38:41], v147 offset:4352
	ds_read_b128 v[42:45], v146 offset:64
	ds_read_b128 v[46:49], v147 offset:64
	v_mul_f32_e32 v18, v145, v19
	v_bfe_u32 v19, v18, 16, 1
	s_waitcnt lgkmcnt(4)
	v_mfma_f32_16x16x32_bf16 v[14:17], v[26:29], v[30:33], v[14:17]
	v_add3_u32 v18, v18, v19, s0
	ds_read_b128 v[50:53], v147 offset:4416
	v_mul_f32_e32 v20, v144, v20
	s_waitcnt lgkmcnt(4)
	v_mfma_f32_16x16x32_bf16 v[6:9], v[34:37], v[30:33], v[6:9]
	v_lshl_add_u64 v[30:31], v[54:55], 0, v[56:57]
	global_store_short_d16_hi v[30:31], v18, off
	v_mul_f32_e32 v18, v145, v23
	v_bfe_u32 v19, v18, 16, 1
	s_waitcnt lgkmcnt(3)
	v_mfma_f32_16x16x32_bf16 v[10:13], v[26:29], v[38:41], v[10:13]
	ds_read_b128 v[26:29], v146 offset:4416
	v_add3_u32 v18, v18, v19, s0
	global_store_short_d16_hi v[30:31], v18, off offset:32
	ds_read_b128 v[30:33], v146 offset:128
	v_mfma_f32_16x16x32_bf16 v[2:5], v[34:37], v[38:41], v[2:5]
	v_lshl_add_u64 v[18:19], s[4:5], 0, v[128:129]
	v_lshlrev_b64 v[18:19], 12, v[18:19]
	v_bfe_u32 v22, v20, 16, 1
	s_waitcnt lgkmcnt(3)
	v_mfma_f32_16x16x32_bf16 v[14:17], v[42:45], v[46:49], v[14:17]
	v_lshl_add_u64 v[18:19], v[54:55], 0, v[18:19]
	v_add3_u32 v20, v20, v22, s0
	s_waitcnt lgkmcnt(2)
	v_mfma_f32_16x16x32_bf16 v[10:13], v[42:45], v[50:53], v[10:13]
	s_waitcnt lgkmcnt(1)
	v_mfma_f32_16x16x32_bf16 v[6:9], v[26:29], v[46:49], v[6:9]
	v_mfma_f32_16x16x32_bf16 v[2:5], v[26:29], v[50:53], v[2:5]
	ds_read_b128 v[26:29], v147 offset:128
	ds_read_b128 v[34:37], v146 offset:4480
	ds_read_b128 v[38:41], v147 offset:4480
	ds_read_b128 v[42:45], v146 offset:192
	ds_read_b128 v[46:49], v147 offset:192
	global_store_short_d16_hi v[18:19], v20, off
	v_mul_f32_e32 v20, v144, v24
	s_waitcnt lgkmcnt(4)
	v_mfma_f32_16x16x32_bf16 v[14:17], v[30:33], v[26:29], v[14:17]
	v_bfe_u32 v22, v20, 16, 1
	v_add3_u32 v20, v20, v22, s0
	global_store_short_d16_hi v[18:19], v20, off offset:32
	v_lshl_add_u64 v[18:19], s[4:5], 0, v[124:125]
	v_mul_f32_e32 v20, v1, v21
	v_lshlrev_b64 v[18:19], 12, v[18:19]
	s_waitcnt lgkmcnt(0)
	v_mfma_f32_16x16x32_bf16 v[14:17], v[42:45], v[46:49], v[14:17]
	v_bfe_u32 v21, v20, 16, 1
	ds_read_b128 v[50:53], v147 offset:4544
	v_lshl_add_u64 v[18:19], v[54:55], 0, v[18:19]
	v_add3_u32 v20, v20, v21, s0
	v_mul_f32_e32 v1, v1, v25
	v_mfma_f32_16x16x32_bf16 v[10:13], v[30:33], v[38:41], v[10:13]
	global_store_short_d16_hi v[18:19], v20, off
	v_bfe_u32 v20, v1, 16, 1
	ds_read_b128 v[30:33], v146 offset:4544
	v_add3_u32 v1, v1, v20, s0
	global_store_short_d16_hi v[18:19], v1, off offset:32
	v_bfe_u32 v1, v14, 16, 1
	v_add3_u32 v1, v14, v1, s0
	v_bfe_u32 v14, v15, 16, 1
	s_waitcnt lgkmcnt(1)
	v_mfma_f32_16x16x32_bf16 v[10:13], v[42:45], v[50:53], v[10:13]
	v_lshrrev_b32_e32 v1, 16, v1
	v_add3_u32 v14, v15, v14, s0
	v_and_or_b32 v14, v14, s1, v1
	v_bfe_u32 v1, v16, 16, 1
	v_mfma_f32_16x16x32_bf16 v[6:9], v[34:37], v[26:29], v[6:9]
	v_add3_u32 v1, v16, v1, s0
	v_bfe_u32 v15, v17, 16, 1
	v_lshrrev_b32_e32 v1, 16, v1
	v_add3_u32 v15, v17, v15, s0
	v_and_or_b32 v15, v15, s1, v1
	v_bfe_u32 v1, v10, 16, 1
	v_add3_u32 v1, v10, v1, s0
	v_bfe_u32 v10, v11, 16, 1
	s_waitcnt lgkmcnt(0)
	v_mfma_f32_16x16x32_bf16 v[6:9], v[30:33], v[46:49], v[6:9]
	v_lshrrev_b32_e32 v1, 16, v1
	v_add3_u32 v10, v11, v10, s0
	v_and_or_b32 v10, v10, s1, v1
	v_bfe_u32 v1, v12, 16, 1
	v_mfma_f32_16x16x32_bf16 v[2:5], v[34:37], v[38:41], v[2:5]
	v_add3_u32 v1, v12, v1, s0
	v_bfe_u32 v11, v13, 16, 1
	v_lshrrev_b32_e32 v1, 16, v1
	v_add3_u32 v11, v13, v11, s0
	v_and_or_b32 v11, v11, s1, v1
	v_bfe_u32 v1, v6, 16, 1
	v_add3_u32 v1, v6, v1, s0
	v_bfe_u32 v6, v7, 16, 1
	v_mfma_f32_16x16x32_bf16 v[2:5], v[30:33], v[50:53], v[2:5]
	v_lshrrev_b32_e32 v1, 16, v1
	v_add3_u32 v6, v7, v6, s0
	v_and_or_b32 v6, v6, s1, v1
	v_bfe_u32 v1, v8, 16, 1
	v_add3_u32 v1, v8, v1, s0
	v_bfe_u32 v7, v9, 16, 1
	v_lshrrev_b32_e32 v1, 16, v1
	v_add3_u32 v7, v9, v7, s0
	v_and_or_b32 v7, v7, s1, v1
	v_bfe_u32 v1, v2, 16, 1
	v_add3_u32 v1, v2, v1, s0
	v_bfe_u32 v2, v3, 16, 1
	v_lshrrev_b32_e32 v1, 16, v1
	v_add3_u32 v2, v3, v2, s0
	v_and_or_b32 v2, v2, s1, v1
	v_bfe_u32 v1, v4, 16, 1
	v_add3_u32 v1, v4, v1, s0
	v_bfe_u32 v3, v5, 16, 1
	v_lshrrev_b32_e32 v1, 16, v1
	v_add3_u32 v3, v5, v3, s0
	v_and_or_b32 v3, v3, s1, v1
	v_add_u32_e32 v1, 0x2000, v131
	s_barrier
	ds_write2_b64 v131, v[14:15], v[6:7] offset1:4
	ds_write2_b64 v1, v[10:11], v[2:3] offset0:32 offset1:36
	s_waitcnt lgkmcnt(0)
	s_barrier
